# v112 + static priority raise for the older co-resident block (bid<256) after each SwiGLU tile (mirror of v116)
# speedup vs baseline: 1.0150x; 1.0150x over previous
; __device__ __forceinline__ float siluf_(float x) { return x * __builtin_amdgcn_rcpf(1.f + __expf(-x)); }
;     ...
;           for (int mi = 0; mi < MI; mi++)
; #pragma unroll
;             for (int ni = 0; ni < 4; ni++)
;               acc[mi][ni] = __builtin_amdgcn_mfma_f32_16x16x32_bf16(bfr[ni], af[mi], acc[mi][ni], 0, 0, 0);
;     ...
;         } else if constexpr (EPI == EPI_SWIGLU) {
; #pragma unroll
;           for (int np = 0; np < 2; np++) {
;             const unsigned hc = ((unsigned)(n0 + wn * 64) >> 1) + np * 16 + fq * 4;
;             const f32x4 g = acc[mi][2 * np], u = acc[mi][2 * np + 1];
;             uint2 o;
;             o.x = pack2(siluf_(g[0]) * u[0], siluf_(g[1]) * u[1]);
;             o.y = pack2(siluf_(g[2]) * u[2], siluf_(g[3]) * u[3]);
;             *(uint2*)(e.b0 + (row * (unsigned)DFF + hc)) = o;
;           }
.Lsw_last:
	v_mfma_f32_16x16x32_bf16 v[134:137], v[194:197], v[156:159], v[134:137]
	v_mfma_f32_16x16x32_bf16 v[130:133], v[198:201], v[156:159], v[130:133]
	v_mfma_f32_16x16x32_bf16 v[126:129], v[202:205], v[156:159], v[126:129]
	v_mfma_f32_16x16x32_bf16 v[122:125], v[226:229], v[156:159], v[122:125]
	v_mfma_f32_16x16x32_bf16 v[118:121], v[194:197], v[166:169], v[118:121]
	v_mfma_f32_16x16x32_bf16 v[114:117], v[198:201], v[166:169], v[114:117]
	v_mfma_f32_16x16x32_bf16 v[110:113], v[202:205], v[166:169], v[110:113]
	v_mfma_f32_16x16x32_bf16 v[106:109], v[226:229], v[166:169], v[106:109]
	v_mfma_f32_16x16x32_bf16 v[102:105], v[194:197], v[170:173], v[102:105]
	v_mfma_f32_16x16x32_bf16 v[98:101], v[198:201], v[170:173], v[98:101]
	v_mfma_f32_16x16x32_bf16 v[94:97], v[202:205], v[170:173], v[94:97]
	v_mfma_f32_16x16x32_bf16 v[90:93], v[226:229], v[170:173], v[90:93]
	v_mfma_f32_16x16x32_bf16 v[86:89], v[194:197], v[174:177], v[86:89]
	v_mfma_f32_16x16x32_bf16 v[82:85], v[198:201], v[174:177], v[82:85]
	v_mfma_f32_16x16x32_bf16 v[78:81], v[202:205], v[174:177], v[78:81]
	v_mfma_f32_16x16x32_bf16 v[74:77], v[226:229], v[174:177], v[74:77]
	v_mfma_f32_16x16x32_bf16 v[70:73], v[194:197], v[178:181], v[70:73]
	v_mfma_f32_16x16x32_bf16 v[66:69], v[198:201], v[178:181], v[66:69]
	v_mfma_f32_16x16x32_bf16 v[62:65], v[202:205], v[178:181], v[62:65]
	v_mfma_f32_16x16x32_bf16 v[58:61], v[226:229], v[178:181], v[58:61]
	v_mfma_f32_16x16x32_bf16 v[54:57], v[194:197], v[182:185], v[54:57]
	v_mfma_f32_16x16x32_bf16 v[50:53], v[198:201], v[182:185], v[50:53]
	v_mfma_f32_16x16x32_bf16 v[46:49], v[202:205], v[182:185], v[46:49]
	v_mfma_f32_16x16x32_bf16 v[42:45], v[226:229], v[182:185], v[42:45]
	v_mfma_f32_16x16x32_bf16 v[38:41], v[194:197], v[186:189], v[38:41]
	v_mfma_f32_16x16x32_bf16 v[34:37], v[198:201], v[186:189], v[34:37]
	v_mfma_f32_16x16x32_bf16 v[30:33], v[202:205], v[186:189], v[30:33]
	v_mfma_f32_16x16x32_bf16 v[26:29], v[226:229], v[186:189], v[26:29]
	v_mfma_f32_16x16x32_bf16 v[22:25], v[194:197], v[190:193], v[22:25]
	v_mfma_f32_16x16x32_bf16 v[18:21], v[198:201], v[190:193], v[18:21]
	v_mfma_f32_16x16x32_bf16 v[14:17], v[202:205], v[190:193], v[14:17]
	v_mfma_f32_16x16x32_bf16 v[10:13], v[226:229], v[190:193], v[10:13]
	s_setprio 2
	v_or_b32_e32 v8, s8, v148
	v_lshrrev_b32_e32 v8, 1, v8
	v_add_u32_e32 v142, s7, v150
	v_or_b32_e32 v8, v8, v149
	s_movk_i32 s4, 0xb00
	v_mad_u64_u32 v[142:143], s[4:5], v142, s4, v[8:9]
	v_bfe_u32 v144, v2, 4, 1
	v_mul_u32_u24_e32 v144, 12, v144
	s_nop 0
	v_add_u32_e32 v142, v142, v144
	v_mul_f32_e32 v174, 0xbfb8aa3b, v134
	v_mul_f32_e32 v175, 0xbfb8aa3b, v135
	v_mul_f32_e32 v176, 0xbfb8aa3b, v136
	v_mul_f32_e32 v177, 0xbfb8aa3b, v137
	v_mul_f32_e32 v178, 0xbfb8aa3b, v126
	v_mul_f32_e32 v179, 0xbfb8aa3b, v127
	v_mul_f32_e32 v180, 0xbfb8aa3b, v128
	v_mul_f32_e32 v181, 0xbfb8aa3b, v129
	v_exp_f32_e32 v174, v174
	v_exp_f32_e32 v175, v175
	v_exp_f32_e32 v176, v176
	v_exp_f32_e32 v177, v177
	v_exp_f32_e32 v178, v178
	v_exp_f32_e32 v179, v179
	v_exp_f32_e32 v180, v180
	v_exp_f32_e32 v181, v181
	v_add_f32_e32 v174, 1.0, v174
	v_add_f32_e32 v175, 1.0, v175
	v_add_f32_e32 v176, 1.0, v176
	v_add_f32_e32 v177, 1.0, v177
	v_add_f32_e32 v178, 1.0, v178
	v_add_f32_e32 v179, 1.0, v179
	v_add_f32_e32 v180, 1.0, v180
	v_add_f32_e32 v181, 1.0, v181
	v_rcp_f32_e32 v174, v174
	v_rcp_f32_e32 v175, v175
	v_rcp_f32_e32 v176, v176
	v_rcp_f32_e32 v177, v177
	v_rcp_f32_e32 v178, v178
	v_rcp_f32_e32 v179, v179
	v_rcp_f32_e32 v180, v180
	v_rcp_f32_e32 v181, v181
	v_mov_b32_e32 v8, v142
	v_pk_mul_f32 v[134:135], v[134:135], v[174:175]
	v_pk_mul_f32 v[136:137], v[136:137], v[176:177]
	v_pk_mul_f32 v[126:127], v[126:127], v[178:179]
	v_pk_mul_f32 v[128:129], v[128:129], v[180:181]
	v_lshl_add_u64 v[182:183], v[8:9], 1, s[52:53]
	v_pk_mul_f32 v[130:131], v[130:131], v[134:135]
	v_pk_mul_f32 v[132:133], v[132:133], v[136:137]
	v_pk_mul_f32 v[122:123], v[122:123], v[126:127]
	v_pk_mul_f32 v[124:125], v[124:125], v[128:129]
	v_cvt_pk_bf16_f32 v166, v130, v131
	v_cvt_pk_bf16_f32 v167, v132, v133
	v_cvt_pk_bf16_f32 v168, v122, v123
	v_cvt_pk_bf16_f32 v169, v124, v125
	s_nop 1
	v_permlane16_swap_b32 v166, v168
	v_permlane16_swap_b32 v167, v169
	s_nop 1
	global_store_dwordx4 v[182:183], v[166:169], off
	v_mul_f32_e32 v174, 0xbfb8aa3b, v118
	v_mul_f32_e32 v175, 0xbfb8aa3b, v119
	v_mul_f32_e32 v176, 0xbfb8aa3b, v120
	v_mul_f32_e32 v177, 0xbfb8aa3b, v121
	v_mul_f32_e32 v178, 0xbfb8aa3b, v110
	v_mul_f32_e32 v179, 0xbfb8aa3b, v111
	v_mul_f32_e32 v180, 0xbfb8aa3b, v112
	v_mul_f32_e32 v181, 0xbfb8aa3b, v113
	v_exp_f32_e32 v174, v174
	v_exp_f32_e32 v175, v175
	v_exp_f32_e32 v176, v176
	v_exp_f32_e32 v177, v177
	v_exp_f32_e32 v178, v178
	v_exp_f32_e32 v179, v179
	v_exp_f32_e32 v180, v180
	v_exp_f32_e32 v181, v181
	v_add_f32_e32 v174, 1.0, v174
	v_add_f32_e32 v175, 1.0, v175
	v_add_f32_e32 v176, 1.0, v176
	v_add_f32_e32 v177, 1.0, v177
	v_add_f32_e32 v178, 1.0, v178
	v_add_f32_e32 v179, 1.0, v179
	v_add_f32_e32 v180, 1.0, v180
	v_add_f32_e32 v181, 1.0, v181
	v_rcp_f32_e32 v174, v174
	v_rcp_f32_e32 v175, v175
	v_rcp_f32_e32 v176, v176
	v_rcp_f32_e32 v177, v177
	v_rcp_f32_e32 v178, v178
	v_rcp_f32_e32 v179, v179
	v_rcp_f32_e32 v180, v180
	v_rcp_f32_e32 v181, v181
	v_add_u32_e32 v8, 0xb000, v142
	v_pk_mul_f32 v[118:119], v[118:119], v[174:175]
	v_pk_mul_f32 v[120:121], v[120:121], v[176:177]
	v_pk_mul_f32 v[110:111], v[110:111], v[178:179]
	v_pk_mul_f32 v[112:113], v[112:113], v[180:181]
	v_lshl_add_u64 v[184:185], v[8:9], 1, s[52:53]
	v_pk_mul_f32 v[114:115], v[114:115], v[118:119]
	v_pk_mul_f32 v[116:117], v[116:117], v[120:121]
	v_pk_mul_f32 v[106:107], v[106:107], v[110:111]
; __device__ __forceinline__ float siluf_(float x) { return x * __builtin_amdgcn_rcpf(1.f + __expf(-x)); }
;     ...
;         } else if constexpr (EPI == EPI_SWIGLU) {
; #pragma unroll
;           for (int np = 0; np < 2; np++) {
;             const unsigned hc = ((unsigned)(n0 + wn * 64) >> 1) + np * 16 + fq * 4;
;             const f32x4 g = acc[mi][2 * np], u = acc[mi][2 * np + 1];
;             uint2 o;
;             o.x = pack2(siluf_(g[0]) * u[0], siluf_(g[1]) * u[1]);
;             o.y = pack2(siluf_(g[2]) * u[2], siluf_(g[3]) * u[3]);
;             *(uint2*)(e.b0 + (row * (unsigned)DFF + hc)) = o;
;           }
	v_pk_mul_f32 v[108:109], v[108:109], v[112:113]
	v_cvt_pk_bf16_f32 v170, v114, v115
	v_cvt_pk_bf16_f32 v171, v116, v117
	v_cvt_pk_bf16_f32 v172, v106, v107
	v_cvt_pk_bf16_f32 v173, v108, v109
	s_nop 1
	v_permlane16_swap_b32 v170, v172
	v_permlane16_swap_b32 v171, v173
	s_nop 1
	global_store_dwordx4 v[184:185], v[170:173], off
	v_mul_f32_e32 v174, 0xbfb8aa3b, v102
	v_mul_f32_e32 v175, 0xbfb8aa3b, v103
	v_mul_f32_e32 v176, 0xbfb8aa3b, v104
	v_mul_f32_e32 v177, 0xbfb8aa3b, v105
	v_mul_f32_e32 v178, 0xbfb8aa3b, v94
	v_mul_f32_e32 v179, 0xbfb8aa3b, v95
	v_mul_f32_e32 v180, 0xbfb8aa3b, v96
	v_mul_f32_e32 v181, 0xbfb8aa3b, v97
	v_exp_f32_e32 v174, v174
	v_exp_f32_e32 v175, v175
	v_exp_f32_e32 v176, v176
	v_exp_f32_e32 v177, v177
	v_exp_f32_e32 v178, v178
	v_exp_f32_e32 v179, v179
	v_exp_f32_e32 v180, v180
	v_exp_f32_e32 v181, v181
	v_add_f32_e32 v174, 1.0, v174
	v_add_f32_e32 v175, 1.0, v175
	v_add_f32_e32 v176, 1.0, v176
	v_add_f32_e32 v177, 1.0, v177
	v_add_f32_e32 v178, 1.0, v178
	v_add_f32_e32 v179, 1.0, v179
	v_add_f32_e32 v180, 1.0, v180
	v_add_f32_e32 v181, 1.0, v181
	v_rcp_f32_e32 v174, v174
	v_rcp_f32_e32 v175, v175
	v_rcp_f32_e32 v176, v176
	v_rcp_f32_e32 v177, v177
	v_rcp_f32_e32 v178, v178
	v_rcp_f32_e32 v179, v179
	v_rcp_f32_e32 v180, v180
	v_rcp_f32_e32 v181, v181
	v_add_u32_e32 v8, 0x16000, v142
	v_pk_mul_f32 v[102:103], v[102:103], v[174:175]
	v_pk_mul_f32 v[104:105], v[104:105], v[176:177]
	v_pk_mul_f32 v[94:95], v[94:95], v[178:179]
	v_pk_mul_f32 v[96:97], v[96:97], v[180:181]
	v_lshl_add_u64 v[182:183], v[8:9], 1, s[52:53]
	v_pk_mul_f32 v[98:99], v[98:99], v[102:103]
	v_pk_mul_f32 v[100:101], v[100:101], v[104:105]
	v_pk_mul_f32 v[90:91], v[90:91], v[94:95]
	v_pk_mul_f32 v[92:93], v[92:93], v[96:97]
	v_cvt_pk_bf16_f32 v166, v98, v99
	v_cvt_pk_bf16_f32 v167, v100, v101
	v_cvt_pk_bf16_f32 v168, v90, v91
	v_cvt_pk_bf16_f32 v169, v92, v93
	s_nop 1
	v_permlane16_swap_b32 v166, v168
	v_permlane16_swap_b32 v167, v169
	s_nop 1
	global_store_dwordx4 v[182:183], v[166:169], off
	v_mul_f32_e32 v174, 0xbfb8aa3b, v86
	v_mul_f32_e32 v175, 0xbfb8aa3b, v87
	v_mul_f32_e32 v176, 0xbfb8aa3b, v88
	v_mul_f32_e32 v177, 0xbfb8aa3b, v89
	v_mul_f32_e32 v178, 0xbfb8aa3b, v78
	v_mul_f32_e32 v179, 0xbfb8aa3b, v79
	v_mul_f32_e32 v180, 0xbfb8aa3b, v80
	v_mul_f32_e32 v181, 0xbfb8aa3b, v81
	v_exp_f32_e32 v174, v174
	v_exp_f32_e32 v175, v175
	v_exp_f32_e32 v176, v176
	v_exp_f32_e32 v177, v177
	v_exp_f32_e32 v178, v178
	v_exp_f32_e32 v179, v179
	v_exp_f32_e32 v180, v180
	v_exp_f32_e32 v181, v181
	v_add_f32_e32 v174, 1.0, v174
	v_add_f32_e32 v175, 1.0, v175
	v_add_f32_e32 v176, 1.0, v176
	v_add_f32_e32 v177, 1.0, v177
	v_add_f32_e32 v178, 1.0, v178
	v_add_f32_e32 v179, 1.0, v179
	v_add_f32_e32 v180, 1.0, v180
	v_add_f32_e32 v181, 1.0, v181
	v_rcp_f32_e32 v174, v174
	v_rcp_f32_e32 v175, v175
	v_rcp_f32_e32 v176, v176
	v_rcp_f32_e32 v177, v177
	v_rcp_f32_e32 v178, v178
	v_rcp_f32_e32 v179, v179
	v_rcp_f32_e32 v180, v180
	v_rcp_f32_e32 v181, v181
	v_add_u32_e32 v8, 0x21000, v142
	v_pk_mul_f32 v[86:87], v[86:87], v[174:175]
	v_pk_mul_f32 v[88:89], v[88:89], v[176:177]
	v_pk_mul_f32 v[78:79], v[78:79], v[178:179]
	v_pk_mul_f32 v[80:81], v[80:81], v[180:181]
	v_lshl_add_u64 v[184:185], v[8:9], 1, s[52:53]
	v_pk_mul_f32 v[82:83], v[82:83], v[86:87]
	v_pk_mul_f32 v[84:85], v[84:85], v[88:89]
	v_pk_mul_f32 v[74:75], v[74:75], v[78:79]
	v_pk_mul_f32 v[76:77], v[76:77], v[80:81]
	v_cvt_pk_bf16_f32 v170, v82, v83
	v_cvt_pk_bf16_f32 v171, v84, v85
	v_cvt_pk_bf16_f32 v172, v74, v75
	v_cvt_pk_bf16_f32 v173, v76, v77
	s_nop 1
	v_permlane16_swap_b32 v170, v172
	v_permlane16_swap_b32 v171, v173
	s_nop 1
	global_store_dwordx4 v[184:185], v[170:173], off
	v_mul_f32_e32 v174, 0xbfb8aa3b, v70
	v_mul_f32_e32 v175, 0xbfb8aa3b, v71
	v_mul_f32_e32 v176, 0xbfb8aa3b, v72
	v_mul_f32_e32 v177, 0xbfb8aa3b, v73
	v_mul_f32_e32 v178, 0xbfb8aa3b, v62
	v_mul_f32_e32 v179, 0xbfb8aa3b, v63
	v_mul_f32_e32 v180, 0xbfb8aa3b, v64
	v_mul_f32_e32 v181, 0xbfb8aa3b, v65
	v_exp_f32_e32 v174, v174
	v_exp_f32_e32 v175, v175
	v_exp_f32_e32 v176, v176
	v_exp_f32_e32 v177, v177
	v_exp_f32_e32 v178, v178
	v_exp_f32_e32 v179, v179
	v_exp_f32_e32 v180, v180
	v_exp_f32_e32 v181, v181
	v_add_f32_e32 v174, 1.0, v174
	v_add_f32_e32 v175, 1.0, v175
	v_add_f32_e32 v176, 1.0, v176
	v_add_f32_e32 v177, 1.0, v177
	v_add_f32_e32 v178, 1.0, v178
	v_add_f32_e32 v179, 1.0, v179
	v_add_f32_e32 v180, 1.0, v180
	v_add_f32_e32 v181, 1.0, v181
	v_rcp_f32_e32 v174, v174
	v_rcp_f32_e32 v175, v175
	v_rcp_f32_e32 v176, v176
	v_rcp_f32_e32 v177, v177
	v_rcp_f32_e32 v178, v178
	v_rcp_f32_e32 v179, v179
	v_rcp_f32_e32 v180, v180
	v_rcp_f32_e32 v181, v181
	v_add_u32_e32 v8, 0x2c000, v142
	v_pk_mul_f32 v[70:71], v[70:71], v[174:175]
	v_pk_mul_f32 v[72:73], v[72:73], v[176:177]
	v_pk_mul_f32 v[62:63], v[62:63], v[178:179]
	v_pk_mul_f32 v[64:65], v[64:65], v[180:181]
	v_lshl_add_u64 v[182:183], v[8:9], 1, s[52:53]
	v_pk_mul_f32 v[66:67], v[66:67], v[70:71]
	v_pk_mul_f32 v[68:69], v[68:69], v[72:73]
	v_pk_mul_f32 v[58:59], v[58:59], v[62:63]
	v_pk_mul_f32 v[60:61], v[60:61], v[64:65]
	v_cvt_pk_bf16_f32 v166, v66, v67
	v_cvt_pk_bf16_f32 v167, v68, v69
	v_cvt_pk_bf16_f32 v168, v58, v59
	v_cvt_pk_bf16_f32 v169, v60, v61
	s_nop 1
; __device__ __forceinline__ float siluf_(float x) { return x * __builtin_amdgcn_rcpf(1.f + __expf(-x)); }
;     ...
;         } else if constexpr (EPI == EPI_SWIGLU) {
; #pragma unroll
;           for (int np = 0; np < 2; np++) {
;             const unsigned hc = ((unsigned)(n0 + wn * 64) >> 1) + np * 16 + fq * 4;
;             const f32x4 g = acc[mi][2 * np], u = acc[mi][2 * np + 1];
;             uint2 o;
;             o.x = pack2(siluf_(g[0]) * u[0], siluf_(g[1]) * u[1]);
;             o.y = pack2(siluf_(g[2]) * u[2], siluf_(g[3]) * u[3]);
;             *(uint2*)(e.b0 + (row * (unsigned)DFF + hc)) = o;
;           }
	v_permlane16_swap_b32 v166, v168
	v_permlane16_swap_b32 v167, v169
	s_nop 1
	global_store_dwordx4 v[182:183], v[166:169], off
	v_mul_f32_e32 v174, 0xbfb8aa3b, v54
	v_mul_f32_e32 v175, 0xbfb8aa3b, v55
	v_mul_f32_e32 v176, 0xbfb8aa3b, v56
	v_mul_f32_e32 v177, 0xbfb8aa3b, v57
	v_mul_f32_e32 v178, 0xbfb8aa3b, v46
	v_mul_f32_e32 v179, 0xbfb8aa3b, v47
	v_mul_f32_e32 v180, 0xbfb8aa3b, v48
	v_mul_f32_e32 v181, 0xbfb8aa3b, v49
	v_exp_f32_e32 v174, v174
	v_exp_f32_e32 v175, v175
	v_exp_f32_e32 v176, v176
	v_exp_f32_e32 v177, v177
	v_exp_f32_e32 v178, v178
	v_exp_f32_e32 v179, v179
	v_exp_f32_e32 v180, v180
	v_exp_f32_e32 v181, v181
	v_add_f32_e32 v174, 1.0, v174
	v_add_f32_e32 v175, 1.0, v175
	v_add_f32_e32 v176, 1.0, v176
	v_add_f32_e32 v177, 1.0, v177
	v_add_f32_e32 v178, 1.0, v178
	v_add_f32_e32 v179, 1.0, v179
	v_add_f32_e32 v180, 1.0, v180
	v_add_f32_e32 v181, 1.0, v181
	v_rcp_f32_e32 v174, v174
	v_rcp_f32_e32 v175, v175
	v_rcp_f32_e32 v176, v176
	v_rcp_f32_e32 v177, v177
	v_rcp_f32_e32 v178, v178
	v_rcp_f32_e32 v179, v179
	v_rcp_f32_e32 v180, v180
	v_rcp_f32_e32 v181, v181
	v_add_u32_e32 v8, 0x37000, v142
	v_pk_mul_f32 v[54:55], v[54:55], v[174:175]
	v_pk_mul_f32 v[56:57], v[56:57], v[176:177]
	v_pk_mul_f32 v[46:47], v[46:47], v[178:179]
	v_pk_mul_f32 v[48:49], v[48:49], v[180:181]
	v_lshl_add_u64 v[184:185], v[8:9], 1, s[52:53]
	v_pk_mul_f32 v[50:51], v[50:51], v[54:55]
	v_pk_mul_f32 v[52:53], v[52:53], v[56:57]
	v_pk_mul_f32 v[42:43], v[42:43], v[46:47]
	v_pk_mul_f32 v[44:45], v[44:45], v[48:49]
	v_cvt_pk_bf16_f32 v170, v50, v51
	v_cvt_pk_bf16_f32 v171, v52, v53
	v_cvt_pk_bf16_f32 v172, v42, v43
	v_cvt_pk_bf16_f32 v173, v44, v45
	s_nop 1
	v_permlane16_swap_b32 v170, v172
	v_permlane16_swap_b32 v171, v173
	s_nop 1
	global_store_dwordx4 v[184:185], v[170:173], off
	v_mul_f32_e32 v174, 0xbfb8aa3b, v38
	v_mul_f32_e32 v175, 0xbfb8aa3b, v39
	v_mul_f32_e32 v176, 0xbfb8aa3b, v40
	v_mul_f32_e32 v177, 0xbfb8aa3b, v41
	v_mul_f32_e32 v178, 0xbfb8aa3b, v30
	v_mul_f32_e32 v179, 0xbfb8aa3b, v31
	v_mul_f32_e32 v180, 0xbfb8aa3b, v32
	v_mul_f32_e32 v181, 0xbfb8aa3b, v33
	v_exp_f32_e32 v174, v174
	v_exp_f32_e32 v175, v175
	v_exp_f32_e32 v176, v176
	v_exp_f32_e32 v177, v177
	v_exp_f32_e32 v178, v178
	v_exp_f32_e32 v179, v179
	v_exp_f32_e32 v180, v180
	v_exp_f32_e32 v181, v181
	v_add_f32_e32 v174, 1.0, v174
	v_add_f32_e32 v175, 1.0, v175
	v_add_f32_e32 v176, 1.0, v176
	v_add_f32_e32 v177, 1.0, v177
	v_add_f32_e32 v178, 1.0, v178
	v_add_f32_e32 v179, 1.0, v179
	v_add_f32_e32 v180, 1.0, v180
	v_add_f32_e32 v181, 1.0, v181
	v_rcp_f32_e32 v174, v174
	v_rcp_f32_e32 v175, v175
	v_rcp_f32_e32 v176, v176
	v_rcp_f32_e32 v177, v177
	v_rcp_f32_e32 v178, v178
	v_rcp_f32_e32 v179, v179
	v_rcp_f32_e32 v180, v180
	v_rcp_f32_e32 v181, v181
	v_add_u32_e32 v8, 0x42000, v142
	v_pk_mul_f32 v[38:39], v[38:39], v[174:175]
	v_pk_mul_f32 v[40:41], v[40:41], v[176:177]
	v_pk_mul_f32 v[30:31], v[30:31], v[178:179]
	v_pk_mul_f32 v[32:33], v[32:33], v[180:181]
	v_lshl_add_u64 v[182:183], v[8:9], 1, s[52:53]
	v_pk_mul_f32 v[34:35], v[34:35], v[38:39]
	v_pk_mul_f32 v[36:37], v[36:37], v[40:41]
	v_pk_mul_f32 v[26:27], v[26:27], v[30:31]
	v_pk_mul_f32 v[28:29], v[28:29], v[32:33]
	v_cvt_pk_bf16_f32 v166, v34, v35
	v_cvt_pk_bf16_f32 v167, v36, v37
	v_cvt_pk_bf16_f32 v168, v26, v27
	v_cvt_pk_bf16_f32 v169, v28, v29
	s_nop 1
	v_permlane16_swap_b32 v166, v168
	v_permlane16_swap_b32 v167, v169
	s_nop 1
	global_store_dwordx4 v[182:183], v[166:169], off
	v_mul_f32_e32 v174, 0xbfb8aa3b, v22
	v_mul_f32_e32 v175, 0xbfb8aa3b, v23
	v_mul_f32_e32 v176, 0xbfb8aa3b, v24
	v_mul_f32_e32 v177, 0xbfb8aa3b, v25
	v_mul_f32_e32 v178, 0xbfb8aa3b, v14
	v_mul_f32_e32 v179, 0xbfb8aa3b, v15
	v_mul_f32_e32 v180, 0xbfb8aa3b, v16
	v_mul_f32_e32 v181, 0xbfb8aa3b, v17
	v_exp_f32_e32 v174, v174
	v_exp_f32_e32 v175, v175
	v_exp_f32_e32 v176, v176
	v_exp_f32_e32 v177, v177
	v_exp_f32_e32 v178, v178
	v_exp_f32_e32 v179, v179
	v_exp_f32_e32 v180, v180
	v_exp_f32_e32 v181, v181
	v_add_f32_e32 v174, 1.0, v174
	v_add_f32_e32 v175, 1.0, v175
	v_add_f32_e32 v176, 1.0, v176
	v_add_f32_e32 v177, 1.0, v177
	v_add_f32_e32 v178, 1.0, v178
	v_add_f32_e32 v179, 1.0, v179
	v_add_f32_e32 v180, 1.0, v180
	v_add_f32_e32 v181, 1.0, v181
	v_rcp_f32_e32 v174, v174
	v_rcp_f32_e32 v175, v175
	v_rcp_f32_e32 v176, v176
	v_rcp_f32_e32 v177, v177
	v_rcp_f32_e32 v178, v178
	v_rcp_f32_e32 v179, v179
	v_rcp_f32_e32 v180, v180
	v_rcp_f32_e32 v181, v181
	v_add_u32_e32 v8, 0x4d000, v142
	v_pk_mul_f32 v[22:23], v[22:23], v[174:175]
	v_pk_mul_f32 v[24:25], v[24:25], v[176:177]
	v_pk_mul_f32 v[14:15], v[14:15], v[178:179]
	v_pk_mul_f32 v[16:17], v[16:17], v[180:181]
	v_lshl_add_u64 v[184:185], v[8:9], 1, s[52:53]
	v_pk_mul_f32 v[18:19], v[18:19], v[22:23]
	v_pk_mul_f32 v[20:21], v[20:21], v[24:25]
	v_pk_mul_f32 v[10:11], v[10:11], v[14:15]
	v_pk_mul_f32 v[12:13], v[12:13], v[16:17]
	v_cvt_pk_bf16_f32 v170, v18, v19
	v_cvt_pk_bf16_f32 v171, v20, v21
	v_cvt_pk_bf16_f32 v172, v10, v11
	v_cvt_pk_bf16_f32 v173, v12, v13
	s_nop 1
	v_permlane16_swap_b32 v170, v172
	v_permlane16_swap_b32 v171, v173
	s_nop 1
	global_store_dwordx4 v[184:185], v[170:173], off
	s_setprio 0
	v_readlane_b32 vcc_lo, v244, 27
	s_nop 0
	s_bitcmp1_b32 vcc_lo, 8
	s_cbranch_scc1 .Lsw_prio_old
	s_setprio 1
